# second resident workgroup of each CU enters the flash loop ~700 cycles late (one softmax segment) so its MFMA segments face the partner's VALU segments
# baseline (speedup 1.0000x reference)
.LBB0_850:
	s_and_b64 s[2:3], s[10:11], exec
	v_readlane_b32 s2, v251, 29
	v_readlane_b32 s3, v251, 30
	s_cselect_b32 s2, s22, 0
	v_writelane_b32 v251, s2, 29
	v_mov_b32_e32 v0, v206
	v_mov_b32_e32 v79, 0
	v_writelane_b32 v251, s3, 30
	s_cmp_gt_u32 s2, s23
	v_mov_b32_e32 v78, 0
	v_mov_b32_e32 v77, 0
	v_mov_b32_e32 v76, 0
	v_mov_b32_e32 v75, 0
	v_mov_b32_e32 v74, 0
	v_mov_b32_e32 v73, 0
	v_mov_b32_e32 v72, 0
	v_mov_b32_e32 v71, 0
	v_mov_b32_e32 v70, 0
	v_mov_b32_e32 v69, 0
	v_mov_b32_e32 v68, 0
	v_mov_b32_e32 v67, 0
	v_mov_b32_e32 v66, 0
	v_mov_b32_e32 v65, 0
	v_mov_b32_e32 v64, 0
	v_mov_b32_e32 v63, 0
	v_mov_b32_e32 v62, 0
	v_mov_b32_e32 v61, 0
	v_mov_b32_e32 v60, 0
	v_mov_b32_e32 v59, 0
	v_mov_b32_e32 v58, 0
	v_mov_b32_e32 v57, 0
	v_mov_b32_e32 v56, 0
	v_mov_b32_e32 v55, 0
	v_mov_b32_e32 v54, 0
	v_mov_b32_e32 v53, 0
	v_mov_b32_e32 v52, 0
	v_mov_b32_e32 v51, 0
	v_mov_b32_e32 v50, 0
	v_mov_b32_e32 v49, 0
	v_mov_b32_e32 v48, 0
	v_mov_b32_e32 v202, 0
	s_cbranch_scc1 .LBB0_869
	v_readlane_b32 s48, v249, 26
	s_lshl_b64 s[14:15], s[0:1], 1
	v_readlane_b32 s50, v249, 28
	v_readlane_b32 s51, v249, 29
	s_add_u32 s0, s50, s14
	s_addc_u32 s1, s51, s15
	v_ashrrev_i32_e32 v8, 4, v0
	s_add_u32 s0, s0, s6
	v_ashrrev_i32_e32 v2, 3, v0
	v_ashrrev_i32_e32 v9, 31, v8
	s_addc_u32 s1, s1, s7
	v_ashrrev_i32_e32 v3, 31, v2
	v_lshlrev_b32_e32 v1, 4, v0
	v_lshlrev_b64 v[10:11], 8, v[8:9]
	v_readlane_b32 s16, v251, 29
	s_and_b64 s[2:3], s[10:11], exec
	v_lshlrev_b64 v[4:5], 7, v[2:3]
	v_lshl_add_u64 v[12:13], s[0:1], 0, v[10:11]
	v_and_b32_e32 v14, 0xf0, v1
	v_mov_b32_e32 v15, v33
	v_readlane_b32 s17, v251, 30
	s_cselect_b32 s25, s24, -1
	v_lshl_add_u64 v[6:7], s[0:1], 0, v[4:5]
	v_lshl_add_u64 v[12:13], v[12:13], 0, v[14:15]
	s_lshl_b64 s[0:1], s[16:17], 14
	v_lshl_add_u64 v[12:13], v[12:13], 0, s[0:1]
	s_mov_b32 s2, 0x803000
	v_add_co_u32_e32 v16, vcc, s2, v12
	s_mov_b32 s2, 0x802000
	s_nop 0
	v_addc_co_u32_e32 v17, vcc, 0, v13, vcc
	v_add_co_u32_e32 v18, vcc, s2, v12
	s_mov_b32 s2, 0x801000
	s_nop 0
	v_addc_co_u32_e32 v19, vcc, 0, v13, vcc
	global_load_dwordx4 v[148:151], v[16:17], off
	global_load_dwordx4 v[152:155], v[18:19], off
	v_add_co_u32_e32 v16, vcc, s2, v12
	v_and_b32_e32 v32, 0x70, v1
	s_nop 0
	v_addc_co_u32_e32 v17, vcc, 0, v13, vcc
	s_mov_b32 s2, 0x800000
	v_lshl_add_u64 v[6:7], v[6:7], 0, v[32:33]
	v_add_co_u32_e32 v12, vcc, s2, v12
	v_lshl_add_u64 v[6:7], v[6:7], 0, s[0:1]
	s_nop 0
	v_addc_co_u32_e32 v13, vcc, 0, v13, vcc
	s_movk_i32 s2, 0x3000
	global_load_dwordx4 v[136:139], v[16:17], off
	global_load_dwordx4 v[140:143], v[12:13], off
	v_add_co_u32_e32 v12, vcc, s2, v6
	s_movk_i32 s2, 0x2000
	s_nop 0
	v_addc_co_u32_e32 v13, vcc, 0, v7, vcc
	v_add_co_u32_e32 v16, vcc, s2, v6
	s_movk_i32 s2, 0x1000
	s_nop 0
	v_addc_co_u32_e32 v17, vcc, 0, v7, vcc
	v_add_co_u32_e32 v18, vcc, s2, v6
	v_mad_u64_u32 v[188:189], s[2:3], v2, s30, v[32:33]
	s_nop 0
	v_addc_co_u32_e32 v19, vcc, 0, v7, vcc
	global_load_dwordx4 v[144:147], v[16:17], off
	global_load_dwordx4 v[132:135], v[18:19], off
	global_load_dwordx4 v[156:159], v[12:13], off
	global_load_dwordx4 v[128:131], v[6:7], off
	v_and_b32_e32 v1, 31, v0
	v_lshrrev_b32_e32 v2, 1, v0
	s_movk_i32 s2, 0x108
	v_and_b32_e32 v6, 16, v2
	v_mul_u32_u24_e32 v7, 0x90, v1
	v_lshrrev_b32_e32 v2, 3, v0
	v_mul_u32_u24_e32 v1, 0x84, v1
	v_mad_u64_u32 v[190:191], s[2:3], v8, s2, v[14:15]
	v_and_b32_e32 v8, 4, v2
	v_lshlrev_b32_e32 v1, 1, v1
	v_lshl_add_u32 v167, v8, 1, v1
	v_lshl_add_u64 v[2:3], s[0:1], 0, v[4:5]
	v_and_b32_e32 v1, 7, v0
	v_lshl_or_b32 v2, v1, 4, v2
	v_lshl_add_u64 v[192:193], s[8:9], 0, v[2:3]
	v_lshl_add_u64 v[2:3], s[0:1], 0, v[10:11]
	v_and_b32_e32 v0, 15, v0
	v_mov_b32_e32 v46, v33
	v_mov_b32_e32 v47, v33
	v_lshl_or_b32 v2, v0, 4, v2
	v_sub_u32_e32 v0, v160, v8
	s_lshl_b32 s0, s16, 7
	v_mov_b32_e32 v32, v33
	v_mov_b32_e32 v34, v33
	v_mov_b32_e32 v35, v33
	v_mov_b32_e32 v36, v33
	v_mov_b32_e32 v37, v33
	v_mov_b32_e32 v38, v33
	v_mov_b32_e32 v39, v33
	v_mov_b32_e32 v40, v33
	v_mov_b32_e32 v41, v33
	v_mov_b32_e32 v42, v33
	v_mov_b32_e32 v43, v33
	v_mov_b32_e32 v44, v33
	v_mov_b32_e32 v45, v33
	v_mov_b64_e32 v[62:63], v[46:47]
	v_mov_b64_e32 v[78:79], v[46:47]
	v_lshl_add_u64 v[194:195], s[8:9], 0, v[2:3]
	s_lshl_b32 s26, s16, 1
	v_subrev_u32_e32 v189, s0, v0
	s_or_b32 s27, s0, 0x7f
	v_mov_b32_e32 v201, 0xf149f2ca
	v_mov_b32_e32 v202, 0
	v_add_u32_e32 v191, v6, v7
	v_mov_b64_e32 v[60:61], v[44:45]
	v_mov_b64_e32 v[58:59], v[42:43]
	v_mov_b64_e32 v[56:57], v[40:41]
	v_mov_b64_e32 v[54:55], v[38:39]
	v_mov_b64_e32 v[52:53], v[36:37]
	v_mov_b64_e32 v[50:51], v[34:35]
	v_mov_b64_e32 v[48:49], v[32:33]
	v_mov_b64_e32 v[76:77], v[44:45]
	v_mov_b64_e32 v[74:75], v[42:43]
	v_mov_b64_e32 v[72:73], v[40:41]
	v_mov_b64_e32 v[70:71], v[38:39]
	v_mov_b64_e32 v[68:69], v[36:37]
	v_mov_b64_e32 v[66:67], v[34:35]
	v_mov_b64_e32 v[64:65], v[32:33]
	v_readlane_b32 s49, v249, 27
	v_readlane_b32 s52, v249, 30
	v_readlane_b32 s53, v249, 31
	v_readlane_b32 s54, v249, 32
	v_readlane_b32 s55, v249, 33
	v_readlane_b32 s56, v249, 34
	v_readlane_b32 s57, v249, 35
	v_readlane_b32 s58, v249, 36
	v_readlane_b32 s59, v249, 37
	v_readlane_b32 s60, v249, 38
	v_readlane_b32 s61, v249, 39
	v_readlane_b32 s62, v249, 40
	v_readlane_b32 s63, v249, 41
	v_readlane_b32 s0, v250, 54
	s_nop 0
	s_cmpk_lt_u32 s0, 0x400
	s_cbranch_scc1 .Lstg_skip
	s_sleep 11
.Lstg_skip:
	s_branch .LBB0_853
